# peeled first K-tile: S1 wait relaxed so the previous epilogue's stores need not be acknowledged before the first MFMA block
# baseline (speedup 1.0000x reference)
; #define PG8_STAGE(bufoff, gbase, voff) do { _Pragma("unroll") for (int _i = 0; _i < 2; ++_i) \
;         __builtin_amdgcn_global_load_lds((const unsigned*)((const char*)(gbase) + (voff)[_i]), (PG8_LAS unsigned*)(lds + (bufoff) + ldsw + _i * 8192), 16, 0, 0); } while (0)
; #define PG8_LDA(dst, b, h) do { _Pragma("unroll") for (int m = 0; m < 4; ++m) _Pragma("unroll") for (int k = 0; k < 2; ++k) dst[m][k] = *(const PG8_LAS bf16x8*)(lds + PG8_SA(b, h) + aoff + m * 2048 + k * 1024); } while (0)
; #define PG8_LDB(dst, b, h) do { _Pragma("unroll") for (int n = 0; n < 2; ++n) _Pragma("unroll") for (int k = 0; k < 2; ++k) dst[n][k] = *(const PG8_LAS bf16x8*)(lds + PG8_SB(b, h) + boff + n * 2048 + k * 1024); } while (0)
; #define PG8_MMA(ai, bj, At, Bt) do { __builtin_amdgcn_s_setprio(1); _Pragma("unroll") for (int m = 0; m < 4; ++m) _Pragma("unroll") for (int n = 0; n < 2; ++n) _Pragma("unroll") for (int k = 0; k < 2; ++k) \
;         acc[ai][bj][m][n] = __builtin_amdgcn_mfma_f32_16x16x32_bf16(Bt[n][k], At[m][k], acc[ai][bj][m][n], 0, 0, 0); __builtin_amdgcn_s_setprio(0); } while (0)
; #define PG8_WAIT_V(n) asm volatile("s_waitcnt vmcnt(" #n ")" ::: "memory")
; #define PG8_WAIT_L(n) asm volatile("s_waitcnt lgkmcnt(" #n ")" ::: "memory")
; template <class Epi, class Sched, bool ALIGN_EPI = false, bool SP2 = true>
; __device__ __forceinline__ void gemm_phase(PG8_LAS unsigned char* lds, const Gemm g, const Sched& S, const Epi& E) {
;     ...
;         const bool has_next = S.next(ui + 1, nxt);
;         const char* nA = has_next ? (const char*)g.A + (size_t)nxt.pm * tstepA + (size_t)nxt.pn * pnA : cA; const char* nB = has_next ? (const char*)g.Bt + (size_t)nxt.pn * tstep : cB;
;         for (int t = 0; t < nt; t += 2) {
;             const bool last = (t == nt - 2);
;             const char* a1 = cA + (size_t)(t + 1) * kstepA;
;             const char* a2 = last ? nA : cA + (size_t)(t + 2) * kstepA; const char* b2 = last ? nB : cB + (size_t)(t + 2) * kstep;
;             const char* a3 = a2 + kstepA; const char* b3 = b2 + kstep;
;             if (last && has_next) S.a_ready(nxt);
;             if constexpr (SP2) {
;             PG8_LDB(B0, 0, 0); PG8_LDB(B1, 0, 1); PG8_SCHED; PG8_LDA(At, 0, 0); PG8_STAGE(PG8_SA(1, 1), a1 + hstepA, voffA);
;             PG8_WAIT_V(8); PG8_WAIT_L(0); PG8_BAR; PG8_MMA(0, 0, At, B0); PG8_MMA(0, 1, At, B1); PG8_BAR; PG8_SCHED;
.LBB0_127:
	s_ashr_i32 s39, s38, 31
	s_lshl_b64 s[6:7], s[38:39], 19
	s_add_u32 s40, s54, s6
	s_addc_u32 s41, s55, s7
	s_and_b64 s[6:7], s[36:37], exec
	s_cselect_b32 s17, s41, s47
	s_cselect_b32 s39, s40, s46
	s_ashr_i32 s25, s24, 31
	s_lshl_b64 s[6:7], s[24:25], 19
	s_add_u32 s42, s26, s6
	s_addc_u32 s43, s27, s7
	s_and_b64 s[6:7], s[36:37], exec
	s_cselect_b32 s25, s43, s49
	s_cselect_b32 s59, s42, s48
	s_add_u32 s46, s46, 0x40080
	s_addc_u32 s47, s47, 0
	s_add_u32 s6, s48, 0x100
	s_addc_u32 s7, s49, 0
	s_mov_b32 s60, -2
	s_waitcnt lgkmcnt(0)
	s_add_u32 s14, s46, 0xfffc0080
	s_addc_u32 s15, s47, -1
	s_add_i32 s70, 0, 0x10000
	s_cmp_eq_u32 s60, 12
	s_cselect_b32 s51, s17, s15
	s_cselect_b32 s50, s39, s14
	v_add_u32_e32 v141, s70, v147
	s_cselect_b32 s49, s25, s7
	s_cselect_b32 s48, s59, s6
	s_add_i32 s71, 0, 0x14000
	ds_read_b128 v[152:155], v141
	ds_read_b128 v[156:159], v141 offset:1024
	ds_read_b128 v[160:163], v141 offset:2048
	ds_read_b128 v[164:167], v141 offset:3072
	v_add_u32_e32 v141, s71, v147
	ds_read_b128 v[168:171], v141
	ds_read_b128 v[172:175], v141 offset:1024
	ds_read_b128 v[176:179], v141 offset:2048
	ds_read_b128 v[180:183], v141 offset:3072
	s_add_u32 s14, s6, 0x3ff80
	s_addc_u32 s15, s7, 0
	v_lshl_add_u64 v[148:149], s[14:15], 0, v[132:133]
	s_add_i32 m0, s28, 0x1c000
	ds_read_b128 v[184:187], v150
	ds_read_b128 v[188:191], v150 offset:1024
	ds_read_b128 v[200:203], v150 offset:2048
	ds_read_b128 v[204:207], v150 offset:3072
	ds_read_b128 v[208:211], v150 offset:4096
	ds_read_b128 v[212:215], v150 offset:5120
	ds_read_b128 v[216:219], v150 offset:6144
	ds_read_b128 v[220:223], v150 offset:7168
	global_load_lds_dwordx4 v[148:149], off
	v_lshl_add_u64 v[148:149], s[14:15], 0, v[128:129]
	s_add_i32 m0, s28, 0x1e000
	s_nop 0
	global_load_lds_dwordx4 v[148:149], off
	v_lshl_add_u64 v[148:149], s[46:47], 0, v[136:137]
	s_add_i32 m0, s29, 0xc000
	s_nop 0
	global_load_lds_dwordx4 v[148:149], off
	v_lshl_add_u64 v[148:149], s[46:47], 0, v[138:139]
	s_add_i32 m0, s29, 0xe000
	s_nop 0
	global_load_lds_dwordx4 v[148:149], off
	s_waitcnt vmcnt(12)
	s_waitcnt lgkmcnt(0)
	s_setprio 1
	s_barrier
	v_mfma_f32_16x16x32_bf16 v[120:123], v[152:155], v[184:187], 0
	v_mfma_f32_16x16x32_bf16 v[112:115], v[160:163], v[184:187], 0
	v_mfma_f32_16x16x32_bf16 v[108:111], v[152:155], v[200:203], 0
	v_mfma_f32_16x16x32_bf16 v[96:99], v[160:163], v[200:203], 0
	v_mfma_f32_16x16x32_bf16 v[92:95], v[152:155], v[208:211], 0
	v_mfma_f32_16x16x32_bf16 v[80:83], v[160:163], v[208:211], 0
	v_mfma_f32_16x16x32_bf16 v[76:79], v[152:155], v[216:219], 0
	v_mfma_f32_16x16x32_bf16 v[64:67], v[160:163], v[216:219], 0
	v_mfma_f32_16x16x32_bf16 v[120:123], v[156:159], v[188:191], v[120:123]
	v_mfma_f32_16x16x32_bf16 v[112:115], v[164:167], v[188:191], v[112:115]
	v_mfma_f32_16x16x32_bf16 v[108:111], v[156:159], v[204:207], v[108:111]
	v_mfma_f32_16x16x32_bf16 v[96:99], v[164:167], v[204:207], v[96:99]
	v_mfma_f32_16x16x32_bf16 v[92:95], v[156:159], v[212:215], v[92:95]
	v_mfma_f32_16x16x32_bf16 v[80:83], v[164:167], v[212:215], v[80:83]
	v_mfma_f32_16x16x32_bf16 v[76:79], v[156:159], v[220:223], v[76:79]
	v_mfma_f32_16x16x32_bf16 v[64:67], v[164:167], v[220:223], v[64:67]
	v_mfma_f32_16x16x32_bf16 v[124:127], v[168:171], v[184:187], 0
	v_mfma_f32_16x16x32_bf16 v[116:119], v[176:179], v[184:187], 0
	v_mfma_f32_16x16x32_bf16 v[104:107], v[168:171], v[200:203], 0
	v_mfma_f32_16x16x32_bf16 v[100:103], v[176:179], v[200:203], 0
	v_mfma_f32_16x16x32_bf16 v[88:91], v[168:171], v[208:211], 0
	v_mfma_f32_16x16x32_bf16 v[84:87], v[176:179], v[208:211], 0
	v_mfma_f32_16x16x32_bf16 v[72:75], v[168:171], v[216:219], 0
	v_mfma_f32_16x16x32_bf16 v[68:71], v[176:179], v[216:219], 0
	v_mfma_f32_16x16x32_bf16 v[124:127], v[172:175], v[188:191], v[124:127]
	v_mfma_f32_16x16x32_bf16 v[116:119], v[180:183], v[188:191], v[116:119]
	v_mfma_f32_16x16x32_bf16 v[104:107], v[172:175], v[204:207], v[104:107]
	v_mfma_f32_16x16x32_bf16 v[100:103], v[180:183], v[204:207], v[100:103]
	v_mfma_f32_16x16x32_bf16 v[88:91], v[172:175], v[212:215], v[88:91]
	v_mfma_f32_16x16x32_bf16 v[84:87], v[180:183], v[212:215], v[84:87]
	v_mfma_f32_16x16x32_bf16 v[72:75], v[172:175], v[220:223], v[72:75]
	v_mfma_f32_16x16x32_bf16 v[68:71], v[180:183], v[220:223], v[68:71]
	s_setprio 0
	s_barrier
; #define PG8_STAGE(bufoff, gbase, voff) do { _Pragma("unroll") for (int _i = 0; _i < 2; ++_i) \
;         __builtin_amdgcn_global_load_lds((const unsigned*)((const char*)(gbase) + (voff)[_i]), (PG8_LAS unsigned*)(lds + (bufoff) + ldsw + _i * 8192), 16, 0, 0); } while (0)
; #define PG8_LDA(dst, b, h) do { _Pragma("unroll") for (int m = 0; m < 4; ++m) _Pragma("unroll") for (int k = 0; k < 2; ++k) dst[m][k] = *(const PG8_LAS bf16x8*)(lds + PG8_SA(b, h) + aoff + m * 2048 + k * 1024); } while (0)
; #define PG8_MMA(ai, bj, At, Bt) do { __builtin_amdgcn_s_setprio(1); _Pragma("unroll") for (int m = 0; m < 4; ++m) _Pragma("unroll") for (int n = 0; n < 2; ++n) _Pragma("unroll") for (int k = 0; k < 2; ++k) \
;         acc[ai][bj][m][n] = __builtin_amdgcn_mfma_f32_16x16x32_bf16(Bt[n][k], At[m][k], acc[ai][bj][m][n], 0, 0, 0); __builtin_amdgcn_s_setprio(0); } while (0)
; #define PG8_WAIT_V(n) asm volatile("s_waitcnt vmcnt(" #n ")" ::: "memory")
; #define PG8_WAIT_L(n) asm volatile("s_waitcnt lgkmcnt(" #n ")" ::: "memory")
; #define PG8_BAR __builtin_amdgcn_s_barrier()
; #define PG8_SCHED __builtin_amdgcn_sched_barrier(0)
; template <class Epi, class Sched, bool ALIGN_EPI = false, bool SP2 = true>
; __device__ __forceinline__ void gemm_phase(PG8_LAS unsigned char* lds, const Gemm g, const Sched& S, const Epi& E) {
;     ...
;             PG8_LDA(At, 0, 1); PG8_STAGE(PG8_SB(0, 0), b2, voffB); PG8_STAGE(PG8_SB(0, 1), b2 + hstep, voffB); PG8_STAGE(PG8_SA(0, 0), a2, voffA);
;             PG8_WAIT_V(8); PG8_WAIT_L(0); PG8_BAR; PG8_MMA(1, 0, At, B0); PG8_MMA(1, 1, At, B1); PG8_BAR; PG8_SCHED;
	s_add_i32 s14, s70, s28
	v_lshl_add_u64 v[148:149], s[48:49], 0, v[132:133]
	s_mov_b32 m0, s14
	ds_read_b128 v[184:187], v150 offset:16384
	ds_read_b128 v[188:191], v150 offset:17408
	ds_read_b128 v[200:203], v150 offset:18432
	ds_read_b128 v[204:207], v150 offset:19456
	ds_read_b128 v[208:211], v150 offset:20480
	ds_read_b128 v[212:215], v150 offset:21504
	ds_read_b128 v[216:219], v150 offset:22528
	ds_read_b128 v[220:223], v150 offset:23552
	global_load_lds_dwordx4 v[148:149], off
	s_add_i32 m0, s14, 0x2000
	v_lshl_add_u64 v[224:225], s[48:49], 0, v[128:129]
	global_load_lds_dwordx4 v[224:225], off
	v_lshl_add_u64 v[234:235], s[50:51], 0, v[130:131]
	v_lshl_add_u64 v[226:227], s[50:51], 0, v[134:135]
	s_mov_b32 m0, s29
	s_nop 0
	global_load_lds_dwordx4 v[226:227], off
	s_mov_b32 m0, s30
	s_nop 0
	global_load_lds_dwordx4 v[234:235], off
	s_waitcnt vmcnt(6)
	s_waitcnt lgkmcnt(0)
	s_setprio 1
	s_barrier
	v_mfma_f32_16x16x32_bf16 v[60:63], v[152:155], v[184:187], 0
	v_mfma_f32_16x16x32_bf16 v[48:51], v[160:163], v[184:187], 0
	v_mfma_f32_16x16x32_bf16 v[44:47], v[152:155], v[200:203], 0
	v_mfma_f32_16x16x32_bf16 v[32:35], v[160:163], v[200:203], 0
	v_mfma_f32_16x16x32_bf16 v[28:31], v[152:155], v[208:211], 0
	v_mfma_f32_16x16x32_bf16 v[16:19], v[160:163], v[208:211], 0
	v_mfma_f32_16x16x32_bf16 v[12:15], v[152:155], v[216:219], 0
	v_mfma_f32_16x16x32_bf16 v[4:7], v[160:163], v[216:219], 0
	v_mfma_f32_16x16x32_bf16 v[60:63], v[156:159], v[188:191], v[60:63]
	v_mfma_f32_16x16x32_bf16 v[48:51], v[164:167], v[188:191], v[48:51]
	v_mfma_f32_16x16x32_bf16 v[44:47], v[156:159], v[204:207], v[44:47]
	v_mfma_f32_16x16x32_bf16 v[32:35], v[164:167], v[204:207], v[32:35]
	v_mfma_f32_16x16x32_bf16 v[28:31], v[156:159], v[212:215], v[28:31]
	v_mfma_f32_16x16x32_bf16 v[16:19], v[164:167], v[212:215], v[16:19]
	v_mfma_f32_16x16x32_bf16 v[12:15], v[156:159], v[220:223], v[12:15]
	v_mfma_f32_16x16x32_bf16 v[4:7], v[164:167], v[220:223], v[4:7]
	v_mfma_f32_16x16x32_bf16 v[56:59], v[168:171], v[184:187], 0
	v_mfma_f32_16x16x32_bf16 v[52:55], v[176:179], v[184:187], 0
	v_mfma_f32_16x16x32_bf16 v[40:43], v[168:171], v[200:203], 0
	v_mfma_f32_16x16x32_bf16 v[36:39], v[176:179], v[200:203], 0
	v_mfma_f32_16x16x32_bf16 v[24:27], v[168:171], v[208:211], 0
	v_mfma_f32_16x16x32_bf16 v[20:23], v[176:179], v[208:211], 0
	v_mfma_f32_16x16x32_bf16 v[8:11], v[168:171], v[216:219], 0
	v_mfma_f32_16x16x32_bf16 v[0:3], v[176:179], v[216:219], 0
	v_mfma_f32_16x16x32_bf16 v[56:59], v[172:175], v[188:191], v[56:59]
	v_mfma_f32_16x16x32_bf16 v[52:55], v[180:183], v[188:191], v[52:55]
	v_mfma_f32_16x16x32_bf16 v[40:43], v[172:175], v[204:207], v[40:43]
	v_mfma_f32_16x16x32_bf16 v[36:39], v[180:183], v[204:207], v[36:39]
	v_mfma_f32_16x16x32_bf16 v[24:27], v[172:175], v[212:215], v[24:27]
	v_mfma_f32_16x16x32_bf16 v[20:23], v[180:183], v[212:215], v[20:23]
	v_mfma_f32_16x16x32_bf16 v[8:11], v[172:175], v[220:223], v[8:11]
	v_mfma_f32_16x16x32_bf16 v[0:3], v[180:183], v[220:223], v[0:3]
	s_setprio 0
	s_barrier
	s_branch .Lgu_s3

; #define PG8_STAGE(bufoff, gbase, voff) do { _Pragma("unroll") for (int _i = 0; _i < 2; ++_i) \
;         __builtin_amdgcn_global_load_lds((const unsigned*)((const char*)(gbase) + (voff)[_i]), (PG8_LAS unsigned*)(lds + (bufoff) + ldsw + _i * 8192), 16, 0, 0); } while (0)
; #define PG8_LDA(dst, b, h) do { _Pragma("unroll") for (int m = 0; m < 4; ++m) _Pragma("unroll") for (int k = 0; k < 2; ++k) dst[m][k] = *(const PG8_LAS bf16x8*)(lds + PG8_SA(b, h) + aoff + m * 2048 + k * 1024); } while (0)
; #define PG8_LDB(dst, b, h) do { _Pragma("unroll") for (int n = 0; n < 2; ++n) _Pragma("unroll") for (int k = 0; k < 2; ++k) dst[n][k] = *(const PG8_LAS bf16x8*)(lds + PG8_SB(b, h) + boff + n * 2048 + k * 1024); } while (0)
; #define PG8_MMA(ai, bj, At, Bt) do { __builtin_amdgcn_s_setprio(1); _Pragma("unroll") for (int m = 0; m < 4; ++m) _Pragma("unroll") for (int n = 0; n < 2; ++n) _Pragma("unroll") for (int k = 0; k < 2; ++k) \
;         acc[ai][bj][m][n] = __builtin_amdgcn_mfma_f32_16x16x32_bf16(Bt[n][k], At[m][k], acc[ai][bj][m][n], 0, 0, 0); __builtin_amdgcn_s_setprio(0); } while (0)
; #define PG8_WAIT_V(n) asm volatile("s_waitcnt vmcnt(" #n ")" ::: "memory")
; #define PG8_WAIT_L(n) asm volatile("s_waitcnt lgkmcnt(" #n ")" ::: "memory")
; #define PG8_BAR __builtin_amdgcn_s_barrier()
; #define PG8_SCHED __builtin_amdgcn_sched_barrier(0)
; template <class Epi, class Sched, bool ALIGN_EPI = false, bool SP2 = true>
; __device__ __forceinline__ void gemm_phase(PG8_LAS unsigned char* lds, const Gemm g, const Sched& S, const Epi& E) {
;     ...
;         for (int t = 0; t < nt; t += 2) {
;             const bool last = (t == nt - 2);
;             const char* a1 = cA + (size_t)(t + 1) * kstepA;
;             const char* a2 = last ? nA : cA + (size_t)(t + 2) * kstepA; const char* b2 = last ? nB : cB + (size_t)(t + 2) * kstep;
;             const char* a3 = a2 + kstepA; const char* b3 = b2 + kstep;
;             if (last && has_next) S.a_ready(nxt);
;             if constexpr (SP2) {
;             PG8_LDB(B0, 0, 0); PG8_LDB(B1, 0, 1); PG8_SCHED; PG8_LDA(At, 0, 0); PG8_STAGE(PG8_SA(1, 1), a1 + hstepA, voffA);
;             PG8_WAIT_V(8); PG8_WAIT_L(0); PG8_BAR; PG8_MMA(0, 0, At, B0); PG8_MMA(0, 1, At, B1); PG8_BAR; PG8_SCHED;
.LBB0_235:
	s_add_u32 s42, s42, 0xc000
	s_addc_u32 s43, s43, 0
	s_add_u32 s17, s46, 0x100
	s_addc_u32 s6, s47, 0
	s_mov_b32 s7, -2
	s_waitcnt lgkmcnt(0)
	s_add_u32 s14, s42, 0x4000
	s_addc_u32 s15, s43, 0
	s_cmp_eq_u32 s7, 40
	s_cselect_b32 s84, s10, s14
	s_cselect_b32 s85, s11, s15
	s_cselect_b32 vcc_lo, s52, s17
	s_cselect_b32 vcc_hi, s53, s6
	s_add_u32 s46, s84, 0x8000
	s_addc_u32 s47, s85, 0
	s_add_i32 s14, 0, 0x10000
	s_add_i32 s4, 0, 0x14000
	v_add_u32_e32 v140, s14, v235
	v_add_u32_e32 v156, s4, v235
	ds_read_b128 v[128:131], v140
	ds_read_b128 v[132:135], v140 offset:1024
	ds_read_b128 v[136:139], v140 offset:2048
	ds_read_b128 v[140:143], v140 offset:3072
	ds_read_b128 v[144:147], v156
	ds_read_b128 v[148:151], v156 offset:1024
	ds_read_b128 v[152:155], v156 offset:2048
	ds_read_b128 v[156:159], v156 offset:3072
	v_lshl_add_u64 v[212:213], s[42:43], 0, v[208:209]
	s_add_i32 m0, s59, 0xc000
	ds_read_b128 v[160:163], v237
	ds_read_b128 v[164:167], v237 offset:1024
	ds_read_b128 v[168:171], v237 offset:2048
	ds_read_b128 v[172:175], v237 offset:3072
	ds_read_b128 v[176:179], v237 offset:4096
	ds_read_b128 v[180:183], v237 offset:5120
	ds_read_b128 v[184:187], v237 offset:6144
	ds_read_b128 v[188:191], v237 offset:7168
	global_load_lds_dwordx4 v[212:213], off
	v_lshl_add_u64 v[212:213], s[42:43], 0, v[210:211]
	s_add_i32 m0, s59, 0xe000
	s_nop 0
	global_load_lds_dwordx4 v[212:213], off
	s_waitcnt vmcnt(40)
	s_waitcnt lgkmcnt(0)
	s_setprio 1
	s_barrier
	v_mfma_f32_16x16x32_bf16 v[124:127], v[128:131], v[160:163], 0
	v_mfma_f32_16x16x32_bf16 v[120:123], v[136:139], v[160:163], 0
	v_mfma_f32_16x16x32_bf16 v[108:111], v[128:131], v[168:171], 0
	v_mfma_f32_16x16x32_bf16 v[104:107], v[136:139], v[168:171], 0
	v_mfma_f32_16x16x32_bf16 v[92:95], v[128:131], v[176:179], 0
	v_mfma_f32_16x16x32_bf16 v[88:91], v[136:139], v[176:179], 0
	v_mfma_f32_16x16x32_bf16 v[76:79], v[128:131], v[184:187], 0
	v_mfma_f32_16x16x32_bf16 v[72:75], v[136:139], v[184:187], 0
	v_mfma_f32_16x16x32_bf16 v[124:127], v[132:135], v[164:167], v[124:127]
	v_mfma_f32_16x16x32_bf16 v[120:123], v[140:143], v[164:167], v[120:123]
	v_mfma_f32_16x16x32_bf16 v[108:111], v[132:135], v[172:175], v[108:111]
	v_mfma_f32_16x16x32_bf16 v[104:107], v[140:143], v[172:175], v[104:107]
	v_mfma_f32_16x16x32_bf16 v[92:95], v[132:135], v[180:183], v[92:95]
	v_mfma_f32_16x16x32_bf16 v[88:91], v[140:143], v[180:183], v[88:91]
	v_mfma_f32_16x16x32_bf16 v[76:79], v[132:135], v[188:191], v[76:79]
	v_mfma_f32_16x16x32_bf16 v[72:75], v[140:143], v[188:191], v[72:75]
	s_setprio 0
	s_setprio 1
	v_mfma_f32_16x16x32_bf16 v[116:119], v[144:147], v[160:163], 0
	v_mfma_f32_16x16x32_bf16 v[112:115], v[152:155], v[160:163], 0
	v_mfma_f32_16x16x32_bf16 v[100:103], v[144:147], v[168:171], 0
	v_mfma_f32_16x16x32_bf16 v[96:99], v[152:155], v[168:171], 0
	v_mfma_f32_16x16x32_bf16 v[84:87], v[144:147], v[176:179], 0
	v_mfma_f32_16x16x32_bf16 v[80:83], v[152:155], v[176:179], 0
	v_mfma_f32_16x16x32_bf16 v[68:71], v[144:147], v[184:187], 0
	v_mfma_f32_16x16x32_bf16 v[64:67], v[152:155], v[184:187], 0
	v_mfma_f32_16x16x32_bf16 v[116:119], v[148:151], v[164:167], v[116:119]
	v_mfma_f32_16x16x32_bf16 v[112:115], v[156:159], v[164:167], v[112:115]
	v_mfma_f32_16x16x32_bf16 v[100:103], v[148:151], v[172:175], v[100:103]
	v_mfma_f32_16x16x32_bf16 v[96:99], v[156:159], v[172:175], v[96:99]
	v_mfma_f32_16x16x32_bf16 v[84:87], v[148:151], v[180:183], v[84:87]
	v_mfma_f32_16x16x32_bf16 v[80:83], v[156:159], v[180:183], v[80:83]
	v_mfma_f32_16x16x32_bf16 v[68:71], v[148:151], v[188:191], v[68:71]
	v_mfma_f32_16x16x32_bf16 v[64:67], v[156:159], v[188:191], v[64:67]
	s_setprio 0
	s_barrier
; #define PG8_STAGE(bufoff, gbase, voff) do { _Pragma("unroll") for (int _i = 0; _i < 2; ++_i) \
;         __builtin_amdgcn_global_load_lds((const unsigned*)((const char*)(gbase) + (voff)[_i]), (PG8_LAS unsigned*)(lds + (bufoff) + ldsw + _i * 8192), 16, 0, 0); } while (0)
; #define PG8_LDA(dst, b, h) do { _Pragma("unroll") for (int m = 0; m < 4; ++m) _Pragma("unroll") for (int k = 0; k < 2; ++k) dst[m][k] = *(const PG8_LAS bf16x8*)(lds + PG8_SA(b, h) + aoff + m * 2048 + k * 1024); } while (0)
; #define PG8_MMA(ai, bj, At, Bt) do { __builtin_amdgcn_s_setprio(1); _Pragma("unroll") for (int m = 0; m < 4; ++m) _Pragma("unroll") for (int n = 0; n < 2; ++n) _Pragma("unroll") for (int k = 0; k < 2; ++k) \
;         acc[ai][bj][m][n] = __builtin_amdgcn_mfma_f32_16x16x32_bf16(Bt[n][k], At[m][k], acc[ai][bj][m][n], 0, 0, 0); __builtin_amdgcn_s_setprio(0); } while (0)
; #define PG8_WAIT_V(n) asm volatile("s_waitcnt vmcnt(" #n ")" ::: "memory")
; #define PG8_WAIT_L(n) asm volatile("s_waitcnt lgkmcnt(" #n ")" ::: "memory")
; #define PG8_BAR __builtin_amdgcn_s_barrier()
; #define PG8_SCHED __builtin_amdgcn_sched_barrier(0)
; template <class Epi, class Sched, bool ALIGN_EPI = false, bool SP2 = true>
; __device__ __forceinline__ void gemm_phase(PG8_LAS unsigned char* lds, const Gemm g, const Sched& S, const Epi& E) {
;     ...
;             PG8_LDA(At, 0, 1); PG8_STAGE(PG8_SB(0, 0), b2, voffB); PG8_STAGE(PG8_SB(0, 1), b2 + hstep, voffB); PG8_STAGE(PG8_SA(0, 0), a2, voffA);
;             PG8_WAIT_V(8); PG8_WAIT_L(0); PG8_BAR; PG8_MMA(1, 0, At, B0); PG8_MMA(1, 1, At, B1); PG8_BAR; PG8_SCHED;
	s_add_i32 s5, s14, s57
	v_lshl_add_u64 v[212:213], vcc, 0, v[194:195]
	s_mov_b32 m0, s5
	ds_read_b128 v[160:163], v237 offset:16384
	ds_read_b128 v[164:167], v237 offset:17408
	ds_read_b128 v[168:171], v237 offset:18432
	ds_read_b128 v[172:175], v237 offset:19456
	ds_read_b128 v[176:179], v237 offset:20480
	ds_read_b128 v[180:183], v237 offset:21504
	ds_read_b128 v[184:187], v237 offset:22528
	ds_read_b128 v[188:191], v237 offset:23552
	global_load_lds_dwordx4 v[212:213], off
	s_add_i32 m0, s5, 0x2000
	s_add_u32 s14, vcc_lo, 0xb0000
	v_lshl_add_u64 v[214:215], vcc, 0, v[204:205]
	s_addc_u32 s15, vcc_hi, 0
	s_add_i32 s4, s4, s57
	global_load_lds_dwordx4 v[214:215], off
	v_lshl_add_u64 v[216:217], s[14:15], 0, v[194:195]
	s_mov_b32 m0, s4
	s_nop 0
	global_load_lds_dwordx4 v[216:217], off
	v_lshl_add_u64 v[216:217], s[14:15], 0, v[204:205]
	s_add_i32 m0, s4, 0x2000
	s_nop 0
	global_load_lds_dwordx4 v[216:217], off
	v_lshl_add_u64 v[216:217], s[84:85], 0, v[200:201]
	s_mov_b32 m0, s59
	s_nop 0
	global_load_lds_dwordx4 v[216:217], off
	v_lshl_add_u64 v[216:217], s[84:85], 0, v[202:203]
	s_mov_b32 m0, s60
	s_nop 0
	global_load_lds_dwordx4 v[216:217], off
	s_waitcnt vmcnt(8)
	s_waitcnt lgkmcnt(0)
	s_setprio 1
	s_barrier
	v_mfma_f32_16x16x32_bf16 v[60:63], v[128:131], v[160:163], 0
	v_mfma_f32_16x16x32_bf16 v[56:59], v[136:139], v[160:163], 0
	v_mfma_f32_16x16x32_bf16 v[44:47], v[128:131], v[168:171], 0
	v_mfma_f32_16x16x32_bf16 v[40:43], v[136:139], v[168:171], 0
	v_mfma_f32_16x16x32_bf16 v[28:31], v[128:131], v[176:179], 0
	v_mfma_f32_16x16x32_bf16 v[24:27], v[136:139], v[176:179], 0
	v_mfma_f32_16x16x32_bf16 v[12:15], v[128:131], v[184:187], 0
	v_mfma_f32_16x16x32_bf16 v[8:11], v[136:139], v[184:187], 0
	v_mfma_f32_16x16x32_bf16 v[60:63], v[132:135], v[164:167], v[60:63]
	v_mfma_f32_16x16x32_bf16 v[56:59], v[140:143], v[164:167], v[56:59]
	v_mfma_f32_16x16x32_bf16 v[44:47], v[132:135], v[172:175], v[44:47]
	v_mfma_f32_16x16x32_bf16 v[40:43], v[140:143], v[172:175], v[40:43]
	v_mfma_f32_16x16x32_bf16 v[28:31], v[132:135], v[180:183], v[28:31]
	v_mfma_f32_16x16x32_bf16 v[24:27], v[140:143], v[180:183], v[24:27]
	v_mfma_f32_16x16x32_bf16 v[12:15], v[132:135], v[188:191], v[12:15]
	v_mfma_f32_16x16x32_bf16 v[8:11], v[140:143], v[188:191], v[8:11]
	s_setprio 0
	s_setprio 1
	v_mfma_f32_16x16x32_bf16 v[52:55], v[144:147], v[160:163], 0
	v_mfma_f32_16x16x32_bf16 v[48:51], v[152:155], v[160:163], 0
	v_mfma_f32_16x16x32_bf16 v[36:39], v[144:147], v[168:171], 0
	v_mfma_f32_16x16x32_bf16 v[32:35], v[152:155], v[168:171], 0
	v_mfma_f32_16x16x32_bf16 v[20:23], v[144:147], v[176:179], 0
	v_mfma_f32_16x16x32_bf16 v[16:19], v[152:155], v[176:179], 0
	v_mfma_f32_16x16x32_bf16 v[4:7], v[144:147], v[184:187], 0
	v_mfma_f32_16x16x32_bf16 v[0:3], v[152:155], v[184:187], 0
	v_mfma_f32_16x16x32_bf16 v[52:55], v[148:151], v[164:167], v[52:55]
	v_mfma_f32_16x16x32_bf16 v[48:51], v[156:159], v[164:167], v[48:51]
	v_mfma_f32_16x16x32_bf16 v[36:39], v[148:151], v[172:175], v[36:39]
	v_mfma_f32_16x16x32_bf16 v[32:35], v[156:159], v[172:175], v[32:35]
	v_mfma_f32_16x16x32_bf16 v[20:23], v[148:151], v[180:183], v[20:23]
	v_mfma_f32_16x16x32_bf16 v[16:19], v[156:159], v[180:183], v[16:19]
	v_mfma_f32_16x16x32_bf16 v[4:7], v[148:151], v[188:191], v[4:7]
	v_mfma_f32_16x16x32_bf16 v[0:3], v[156:159], v[188:191], v[0:3]
	s_setprio 0
	s_barrier
	s_branch .Ldn_s3

; #define PG8_STAGE(bufoff, gbase, voff) do { _Pragma("unroll") for (int _i = 0; _i < 2; ++_i) \
;         __builtin_amdgcn_global_load_lds((const unsigned*)((const char*)(gbase) + (voff)[_i]), (PG8_LAS unsigned*)(lds + (bufoff) + ldsw + _i * 8192), 16, 0, 0); } while (0)
; #define PG8_LDA(dst, b, h) do { _Pragma("unroll") for (int m = 0; m < 4; ++m) _Pragma("unroll") for (int k = 0; k < 2; ++k) dst[m][k] = *(const PG8_LAS bf16x8*)(lds + PG8_SA(b, h) + aoff + m * 2048 + k * 1024); } while (0)
; #define PG8_LDB(dst, b, h) do { _Pragma("unroll") for (int n = 0; n < 2; ++n) _Pragma("unroll") for (int k = 0; k < 2; ++k) dst[n][k] = *(const PG8_LAS bf16x8*)(lds + PG8_SB(b, h) + boff + n * 2048 + k * 1024); } while (0)
; #define PG8_MMA(ai, bj, At, Bt) do { __builtin_amdgcn_s_setprio(1); _Pragma("unroll") for (int m = 0; m < 4; ++m) _Pragma("unroll") for (int n = 0; n < 2; ++n) _Pragma("unroll") for (int k = 0; k < 2; ++k) \
;         acc[ai][bj][m][n] = __builtin_amdgcn_mfma_f32_16x16x32_bf16(Bt[n][k], At[m][k], acc[ai][bj][m][n], 0, 0, 0); __builtin_amdgcn_s_setprio(0); } while (0)
; #define PG8_WAIT_V(n) asm volatile("s_waitcnt vmcnt(" #n ")" ::: "memory")
; #define PG8_WAIT_L(n) asm volatile("s_waitcnt lgkmcnt(" #n ")" ::: "memory")
; template <class Epi, class Sched, bool ALIGN_EPI = false, bool SP2 = true>
; __device__ __forceinline__ void gemm_phase(PG8_LAS unsigned char* lds, const Gemm g, const Sched& S, const Epi& E) {
;     ...
;         const bool has_next = S.next(ui + 1, nxt);
;         const char* nA = has_next ? (const char*)g.A + (size_t)nxt.pm * tstepA + (size_t)nxt.pn * pnA : cA; const char* nB = has_next ? (const char*)g.Bt + (size_t)nxt.pn * tstep : cB;
;         for (int t = 0; t < nt; t += 2) {
;             const bool last = (t == nt - 2);
;             const char* a1 = cA + (size_t)(t + 1) * kstepA;
;             const char* a2 = last ? nA : cA + (size_t)(t + 2) * kstepA; const char* b2 = last ? nB : cB + (size_t)(t + 2) * kstep;
;             const char* a3 = a2 + kstepA; const char* b3 = b2 + kstep;
;             if (last && has_next) S.a_ready(nxt);
;             if constexpr (SP2) {
;             PG8_LDB(B0, 0, 0); PG8_LDB(B1, 0, 1); PG8_SCHED; PG8_LDA(At, 0, 0); PG8_STAGE(PG8_SA(1, 1), a1 + hstepA, voffA);
;             PG8_WAIT_V(8); PG8_WAIT_L(0); PG8_BAR; PG8_MMA(0, 0, At, B0); PG8_MMA(0, 1, At, B1); PG8_BAR; PG8_SCHED;
.LBB0_375:
	s_ashr_i32 s41, s40, 31
	s_lshl_b64 s[6:7], s[40:41], 19
	s_add_u32 s42, s54, s6
	s_addc_u32 s43, s55, s7
	s_and_b64 s[6:7], s[36:37], exec
	s_cselect_b32 s16, s43, s53
	s_cselect_b32 s17, s42, s52
	s_ashr_i32 s39, s38, 31
	s_lshl_b64 s[6:7], s[38:39], 19
	s_add_u32 s44, s10, s6
	s_addc_u32 s45, s11, s7
	s_and_b64 s[6:7], s[36:37], exec
	s_cselect_b32 s39, s45, s47
	s_cselect_b32 s41, s44, s46
	s_add_u32 s52, s52, 0x40080
	s_addc_u32 s53, s53, 0
	s_add_u32 s6, s46, 0x100
	s_addc_u32 s7, s47, 0
	s_mov_b32 s59, -2
	s_add_u32 s4, s52, 0xfffc0080
	s_addc_u32 s5, s53, -1
	s_add_i32 s14, 0, 0x10000
	s_cmp_eq_u32 s59, 12
	s_cselect_b32 s85, s16, s5
	s_cselect_b32 s84, s17, s4
	v_add_u32_e32 v138, s14, v145
	s_cselect_b32 s47, s39, s7
	s_cselect_b32 s46, s41, s6
	s_add_i32 s4, 0, 0x14000
	ds_read_b128 v[150:153], v138
	ds_read_b128 v[154:157], v138 offset:1024
	ds_read_b128 v[158:161], v138 offset:2048
	ds_read_b128 v[162:165], v138 offset:3072
	v_add_u32_e32 v138, s4, v145
	ds_read_b128 v[166:169], v138
	ds_read_b128 v[170:173], v138 offset:1024
	ds_read_b128 v[174:177], v138 offset:2048
	ds_read_b128 v[178:181], v138 offset:3072
	v_lshl_add_u64 v[138:139], s[52:53], 0, v[134:135]
	s_add_i32 m0, s31, 0xc000
	ds_read_b128 v[182:185], v149
	ds_read_b128 v[186:189], v149 offset:1024
	ds_read_b128 v[200:203], v149 offset:2048
	ds_read_b128 v[204:207], v149 offset:3072
	ds_read_b128 v[208:211], v149 offset:4096
	ds_read_b128 v[212:215], v149 offset:5120
	ds_read_b128 v[216:219], v149 offset:6144
	ds_read_b128 v[220:223], v149 offset:7168
	global_load_lds_dwordx4 v[138:139], off
	v_lshl_add_u64 v[138:139], s[52:53], 0, v[136:137]
	s_add_i32 m0, s31, 0xe000
	s_nop 0
	global_load_lds_dwordx4 v[138:139], off
	s_waitcnt vmcnt(24)
	s_waitcnt lgkmcnt(0)
	s_setprio 1
	s_barrier
	v_mfma_f32_16x16x32_bf16 v[124:127], v[150:153], v[182:185], 0
	v_mfma_f32_16x16x32_bf16 v[120:123], v[158:161], v[182:185], 0
	v_mfma_f32_16x16x32_bf16 v[112:115], v[150:153], v[200:203], 0
	v_mfma_f32_16x16x32_bf16 v[104:107], v[158:161], v[200:203], 0
	v_mfma_f32_16x16x32_bf16 v[96:99], v[150:153], v[208:211], 0
	v_mfma_f32_16x16x32_bf16 v[88:91], v[158:161], v[208:211], 0
	v_mfma_f32_16x16x32_bf16 v[80:83], v[150:153], v[216:219], 0
	v_mfma_f32_16x16x32_bf16 v[72:75], v[158:161], v[216:219], 0
	v_mfma_f32_16x16x32_bf16 v[124:127], v[154:157], v[186:189], v[124:127]
	v_mfma_f32_16x16x32_bf16 v[120:123], v[162:165], v[186:189], v[120:123]
	v_mfma_f32_16x16x32_bf16 v[112:115], v[154:157], v[204:207], v[112:115]
	v_mfma_f32_16x16x32_bf16 v[104:107], v[162:165], v[204:207], v[104:107]
	v_mfma_f32_16x16x32_bf16 v[96:99], v[154:157], v[212:215], v[96:99]
	v_mfma_f32_16x16x32_bf16 v[88:91], v[162:165], v[212:215], v[88:91]
	v_mfma_f32_16x16x32_bf16 v[80:83], v[154:157], v[220:223], v[80:83]
	v_mfma_f32_16x16x32_bf16 v[72:75], v[162:165], v[220:223], v[72:75]
	s_setprio 0
	s_setprio 1
	v_mfma_f32_16x16x32_bf16 v[116:119], v[166:169], v[182:185], 0
	v_mfma_f32_16x16x32_bf16 v[108:111], v[174:177], v[182:185], 0
	v_mfma_f32_16x16x32_bf16 v[100:103], v[166:169], v[200:203], 0
	v_mfma_f32_16x16x32_bf16 v[92:95], v[174:177], v[200:203], 0
	v_mfma_f32_16x16x32_bf16 v[84:87], v[166:169], v[208:211], 0
	v_mfma_f32_16x16x32_bf16 v[76:79], v[174:177], v[208:211], 0
	v_mfma_f32_16x16x32_bf16 v[68:71], v[166:169], v[216:219], 0
	v_mfma_f32_16x16x32_bf16 v[64:67], v[174:177], v[216:219], 0
	v_mfma_f32_16x16x32_bf16 v[116:119], v[170:173], v[186:189], v[116:119]
	v_mfma_f32_16x16x32_bf16 v[108:111], v[178:181], v[186:189], v[108:111]
	v_mfma_f32_16x16x32_bf16 v[100:103], v[170:173], v[204:207], v[100:103]
	v_mfma_f32_16x16x32_bf16 v[92:95], v[178:181], v[204:207], v[92:95]
	v_mfma_f32_16x16x32_bf16 v[84:87], v[170:173], v[212:215], v[84:87]
	v_mfma_f32_16x16x32_bf16 v[76:79], v[178:181], v[212:215], v[76:79]
	v_mfma_f32_16x16x32_bf16 v[68:71], v[170:173], v[220:223], v[68:71]
	v_mfma_f32_16x16x32_bf16 v[64:67], v[178:181], v[220:223], v[64:67]
	s_setprio 0
	s_barrier
; #define PG8_STAGE(bufoff, gbase, voff) do { _Pragma("unroll") for (int _i = 0; _i < 2; ++_i) \
;         __builtin_amdgcn_global_load_lds((const unsigned*)((const char*)(gbase) + (voff)[_i]), (PG8_LAS unsigned*)(lds + (bufoff) + ldsw + _i * 8192), 16, 0, 0); } while (0)
; #define PG8_LDA(dst, b, h) do { _Pragma("unroll") for (int m = 0; m < 4; ++m) _Pragma("unroll") for (int k = 0; k < 2; ++k) dst[m][k] = *(const PG8_LAS bf16x8*)(lds + PG8_SA(b, h) + aoff + m * 2048 + k * 1024); } while (0)
; #define PG8_MMA(ai, bj, At, Bt) do { __builtin_amdgcn_s_setprio(1); _Pragma("unroll") for (int m = 0; m < 4; ++m) _Pragma("unroll") for (int n = 0; n < 2; ++n) _Pragma("unroll") for (int k = 0; k < 2; ++k) \
;         acc[ai][bj][m][n] = __builtin_amdgcn_mfma_f32_16x16x32_bf16(Bt[n][k], At[m][k], acc[ai][bj][m][n], 0, 0, 0); __builtin_amdgcn_s_setprio(0); } while (0)
; #define PG8_WAIT_V(n) asm volatile("s_waitcnt vmcnt(" #n ")" ::: "memory")
; #define PG8_WAIT_L(n) asm volatile("s_waitcnt lgkmcnt(" #n ")" ::: "memory")
; #define PG8_BAR __builtin_amdgcn_s_barrier()
; #define PG8_SCHED __builtin_amdgcn_sched_barrier(0)
; template <class Epi, class Sched, bool ALIGN_EPI = false, bool SP2 = true>
; __device__ __forceinline__ void gemm_phase(PG8_LAS unsigned char* lds, const Gemm g, const Sched& S, const Epi& E) {
;     ...
;             PG8_LDA(At, 0, 1); PG8_STAGE(PG8_SB(0, 0), b2, voffB); PG8_STAGE(PG8_SB(0, 1), b2 + hstep, voffB); PG8_STAGE(PG8_SA(0, 0), a2, voffA);
;             PG8_WAIT_V(8); PG8_WAIT_L(0); PG8_BAR; PG8_MMA(1, 0, At, B0); PG8_MMA(1, 1, At, B1); PG8_BAR; PG8_SCHED;
	s_add_i32 s5, s14, s28
	v_lshl_add_u64 v[138:139], s[46:47], 0, v[194:195]
	s_mov_b32 m0, s5
	ds_read_b128 v[182:185], v149 offset:16384
	ds_read_b128 v[186:189], v149 offset:17408
	ds_read_b128 v[200:203], v149 offset:18432
	ds_read_b128 v[204:207], v149 offset:19456
	ds_read_b128 v[208:211], v149 offset:20480
	ds_read_b128 v[212:215], v149 offset:21504
	ds_read_b128 v[216:219], v149 offset:22528
	ds_read_b128 v[220:223], v149 offset:23552
	global_load_lds_dwordx4 v[138:139], off
	s_add_i32 m0, s5, 0x2000
	s_add_u32 s14, s46, 0x40000
	v_lshl_add_u64 v[142:143], s[46:47], 0, v[128:129]
	s_addc_u32 s15, s47, 0
	s_add_i32 s4, s4, s28
	global_load_lds_dwordx4 v[142:143], off
	v_lshl_add_u64 v[190:191], s[14:15], 0, v[194:195]
	s_mov_b32 m0, s4
	v_lshl_add_u64 v[224:225], s[84:85], 0, v[130:131]
	global_load_lds_dwordx4 v[190:191], off
	v_lshl_add_u64 v[190:191], s[14:15], 0, v[128:129]
	s_add_i32 m0, s4, 0x2000
	s_nop 0
	global_load_lds_dwordx4 v[190:191], off
	v_lshl_add_u64 v[190:191], s[84:85], 0, v[132:133]
	s_mov_b32 m0, s31
	s_nop 0
	global_load_lds_dwordx4 v[190:191], off
	s_mov_b32 m0, s34
	s_nop 0
	global_load_lds_dwordx4 v[224:225], off
	s_waitcnt vmcnt(8)
	s_waitcnt lgkmcnt(0)
	s_setprio 1
	s_barrier
	v_mfma_f32_16x16x32_bf16 v[60:63], v[150:153], v[182:185], 0
	v_mfma_f32_16x16x32_bf16 v[56:59], v[158:161], v[182:185], 0
	v_mfma_f32_16x16x32_bf16 v[48:51], v[150:153], v[200:203], 0
	v_mfma_f32_16x16x32_bf16 v[40:43], v[158:161], v[200:203], 0
	v_mfma_f32_16x16x32_bf16 v[32:35], v[150:153], v[208:211], 0
	v_mfma_f32_16x16x32_bf16 v[24:27], v[158:161], v[208:211], 0
	v_mfma_f32_16x16x32_bf16 v[16:19], v[150:153], v[216:219], 0
	v_mfma_f32_16x16x32_bf16 v[8:11], v[158:161], v[216:219], 0
	v_mfma_f32_16x16x32_bf16 v[60:63], v[154:157], v[186:189], v[60:63]
	v_mfma_f32_16x16x32_bf16 v[56:59], v[162:165], v[186:189], v[56:59]
	v_mfma_f32_16x16x32_bf16 v[48:51], v[154:157], v[204:207], v[48:51]
	v_mfma_f32_16x16x32_bf16 v[40:43], v[162:165], v[204:207], v[40:43]
	v_mfma_f32_16x16x32_bf16 v[32:35], v[154:157], v[212:215], v[32:35]
	v_mfma_f32_16x16x32_bf16 v[24:27], v[162:165], v[212:215], v[24:27]
	v_mfma_f32_16x16x32_bf16 v[16:19], v[154:157], v[220:223], v[16:19]
	v_mfma_f32_16x16x32_bf16 v[8:11], v[162:165], v[220:223], v[8:11]
	s_setprio 0
	s_setprio 1
	v_mfma_f32_16x16x32_bf16 v[52:55], v[166:169], v[182:185], 0
	v_mfma_f32_16x16x32_bf16 v[44:47], v[174:177], v[182:185], 0
	v_mfma_f32_16x16x32_bf16 v[36:39], v[166:169], v[200:203], 0
	v_mfma_f32_16x16x32_bf16 v[28:31], v[174:177], v[200:203], 0
	v_mfma_f32_16x16x32_bf16 v[20:23], v[166:169], v[208:211], 0
	v_mfma_f32_16x16x32_bf16 v[12:15], v[174:177], v[208:211], 0
	v_mfma_f32_16x16x32_bf16 v[4:7], v[166:169], v[216:219], 0
	v_mfma_f32_16x16x32_bf16 v[0:3], v[174:177], v[216:219], 0
	v_mfma_f32_16x16x32_bf16 v[52:55], v[170:173], v[186:189], v[52:55]
	v_mfma_f32_16x16x32_bf16 v[44:47], v[178:181], v[186:189], v[44:47]
	v_mfma_f32_16x16x32_bf16 v[36:39], v[170:173], v[204:207], v[36:39]
	v_mfma_f32_16x16x32_bf16 v[28:31], v[178:181], v[204:207], v[28:31]
	v_mfma_f32_16x16x32_bf16 v[20:23], v[170:173], v[212:215], v[20:23]
	v_mfma_f32_16x16x32_bf16 v[12:15], v[178:181], v[212:215], v[12:15]
	v_mfma_f32_16x16x32_bf16 v[4:7], v[170:173], v[220:223], v[4:7]
	v_mfma_f32_16x16x32_bf16 v[0:3], v[178:181], v[220:223], v[0:3]
	s_setprio 0
	s_barrier
	s_branch .Lmi_s3

; #define PG8_STAGE(bufoff, gbase, voff) do { _Pragma("unroll") for (int _i = 0; _i < 2; ++_i) \
;         __builtin_amdgcn_global_load_lds((const unsigned*)((const char*)(gbase) + (voff)[_i]), (PG8_LAS unsigned*)(lds + (bufoff) + ldsw + _i * 8192), 16, 0, 0); } while (0)
; #define PG8_LDA(dst, b, h) do { _Pragma("unroll") for (int m = 0; m < 4; ++m) _Pragma("unroll") for (int k = 0; k < 2; ++k) dst[m][k] = *(const PG8_LAS bf16x8*)(lds + PG8_SA(b, h) + aoff + m * 2048 + k * 1024); } while (0)
; #define PG8_LDB(dst, b, h) do { _Pragma("unroll") for (int n = 0; n < 2; ++n) _Pragma("unroll") for (int k = 0; k < 2; ++k) dst[n][k] = *(const PG8_LAS bf16x8*)(lds + PG8_SB(b, h) + boff + n * 2048 + k * 1024); } while (0)
; #define PG8_MMA(ai, bj, At, Bt) do { __builtin_amdgcn_s_setprio(1); _Pragma("unroll") for (int m = 0; m < 4; ++m) _Pragma("unroll") for (int n = 0; n < 2; ++n) _Pragma("unroll") for (int k = 0; k < 2; ++k) \
;         acc[ai][bj][m][n] = __builtin_amdgcn_mfma_f32_16x16x32_bf16(Bt[n][k], At[m][k], acc[ai][bj][m][n], 0, 0, 0); __builtin_amdgcn_s_setprio(0); } while (0)
; #define PG8_WAIT_V(n) asm volatile("s_waitcnt vmcnt(" #n ")" ::: "memory")
; #define PG8_WAIT_L(n) asm volatile("s_waitcnt lgkmcnt(" #n ")" ::: "memory")
; template <class Epi, class Sched, bool ALIGN_EPI = false, bool SP2 = true>
; __device__ __forceinline__ void gemm_phase(PG8_LAS unsigned char* lds, const Gemm g, const Sched& S, const Epi& E) {
;     ...
;         const bool has_next = S.next(ui + 1, nxt);
;         const char* nA = has_next ? (const char*)g.A + (size_t)nxt.pm * tstepA + (size_t)nxt.pn * pnA : cA; const char* nB = has_next ? (const char*)g.Bt + (size_t)nxt.pn * tstep : cB;
;         for (int t = 0; t < nt; t += 2) {
;             const bool last = (t == nt - 2);
;             const char* a1 = cA + (size_t)(t + 1) * kstepA;
;             const char* a2 = last ? nA : cA + (size_t)(t + 2) * kstepA; const char* b2 = last ? nB : cB + (size_t)(t + 2) * kstep;
;             const char* a3 = a2 + kstepA; const char* b3 = b2 + kstep;
;             if (last && has_next) S.a_ready(nxt);
;             if constexpr (SP2) {
;             PG8_LDB(B0, 0, 0); PG8_LDB(B1, 0, 1); PG8_SCHED; PG8_LDA(At, 0, 0); PG8_STAGE(PG8_SA(1, 1), a1 + hstepA, voffA);
;             PG8_WAIT_V(8); PG8_WAIT_L(0); PG8_BAR; PG8_MMA(0, 0, At, B0); PG8_MMA(0, 1, At, B1); PG8_BAR; PG8_SCHED;
.LBB0_744:
	s_ashr_i32 s41, s40, 31
	s_lshl_b64 s[6:7], s[40:41], 19
	s_add_u32 s42, s26, s6
	s_addc_u32 s43, s27, s7
	s_and_b64 s[6:7], s[38:39], exec
	s_cselect_b32 s16, s43, s51
	s_cselect_b32 s17, s42, s50
	s_ashr_i32 s25, s24, 31
	s_lshl_b64 s[6:7], s[24:25], 19
	s_add_u32 s44, s28, s6
	s_addc_u32 s45, s29, s7
	s_and_b64 s[6:7], s[38:39], exec
	s_cselect_b32 s25, s45, s53
	s_cselect_b32 s41, s44, s52
	s_add_u32 s50, s50, 0x40080
	s_addc_u32 s51, s51, 0
	s_add_u32 s6, s52, 0x100
	s_addc_u32 s7, s53, 0
	s_mov_b32 s47, -2
	s_add_u32 s4, s50, 0xfffc0080
	s_addc_u32 s5, s51, -1
	s_add_i32 s14, 0, 0x10000
	s_cmp_eq_u32 s47, 12
	s_cselect_b32 s85, s16, s5
	s_cselect_b32 s84, s17, s4
	s_cselect_b32 s53, s25, s7
	s_cselect_b32 s52, s41, s6
	s_add_i32 s4, 0, 0x14000
	v_add_u32_e32 v146, s14, v173
	v_add_u32_e32 v162, s4, v173
	ds_read_b128 v[134:137], v146
	ds_read_b128 v[138:141], v146 offset:1024
	ds_read_b128 v[142:145], v146 offset:2048
	ds_read_b128 v[146:149], v146 offset:3072
	ds_read_b128 v[150:153], v162
	ds_read_b128 v[154:157], v162 offset:1024
	ds_read_b128 v[158:161], v162 offset:2048
	ds_read_b128 v[162:165], v162 offset:3072
	v_lshl_add_u64 v[170:171], s[50:51], 0, v[130:131]
	s_add_i32 m0, s31, 0xc000
	ds_read_b128 v[166:169], v175
	ds_read_b128 v[176:179], v175 offset:1024
	ds_read_b128 v[180:183], v175 offset:2048
	ds_read_b128 v[184:187], v175 offset:3072
	ds_read_b128 v[188:191], v175 offset:4096
	ds_read_b128 v[200:203], v175 offset:5120
	ds_read_b128 v[204:207], v175 offset:6144
	ds_read_b128 v[208:211], v175 offset:7168
	global_load_lds_dwordx4 v[170:171], off
	v_lshl_add_u64 v[170:171], s[50:51], 0, v[132:133]
	s_add_i32 m0, s31, 0xe000
	s_nop 0
	global_load_lds_dwordx4 v[170:171], off
	s_waitcnt vmcnt(48)
	s_waitcnt lgkmcnt(0)
	s_setprio 1
	s_barrier
	v_mfma_f32_16x16x32_bf16 v[124:127], v[134:137], v[166:169], 0
	v_mfma_f32_16x16x32_bf16 v[120:123], v[142:145], v[166:169], 0
	v_mfma_f32_16x16x32_bf16 v[108:111], v[134:137], v[180:183], 0
	v_mfma_f32_16x16x32_bf16 v[104:107], v[142:145], v[180:183], 0
	v_mfma_f32_16x16x32_bf16 v[92:95], v[134:137], v[188:191], 0
	v_mfma_f32_16x16x32_bf16 v[88:91], v[142:145], v[188:191], 0
	v_mfma_f32_16x16x32_bf16 v[76:79], v[134:137], v[204:207], 0
	v_mfma_f32_16x16x32_bf16 v[72:75], v[142:145], v[204:207], 0
	v_mfma_f32_16x16x32_bf16 v[124:127], v[138:141], v[176:179], v[124:127]
	v_mfma_f32_16x16x32_bf16 v[120:123], v[146:149], v[176:179], v[120:123]
	v_mfma_f32_16x16x32_bf16 v[108:111], v[138:141], v[184:187], v[108:111]
	v_mfma_f32_16x16x32_bf16 v[104:107], v[146:149], v[184:187], v[104:107]
	v_mfma_f32_16x16x32_bf16 v[92:95], v[138:141], v[200:203], v[92:95]
	v_mfma_f32_16x16x32_bf16 v[88:91], v[146:149], v[200:203], v[88:91]
	v_mfma_f32_16x16x32_bf16 v[76:79], v[138:141], v[208:211], v[76:79]
	v_mfma_f32_16x16x32_bf16 v[72:75], v[146:149], v[208:211], v[72:75]
	s_setprio 0
	s_setprio 1
	v_mfma_f32_16x16x32_bf16 v[116:119], v[150:153], v[166:169], 0
	v_mfma_f32_16x16x32_bf16 v[112:115], v[158:161], v[166:169], 0
	v_mfma_f32_16x16x32_bf16 v[100:103], v[150:153], v[180:183], 0
	v_mfma_f32_16x16x32_bf16 v[96:99], v[158:161], v[180:183], 0
	v_mfma_f32_16x16x32_bf16 v[84:87], v[150:153], v[188:191], 0
	v_mfma_f32_16x16x32_bf16 v[80:83], v[158:161], v[188:191], 0
	v_mfma_f32_16x16x32_bf16 v[68:71], v[150:153], v[204:207], 0
	v_mfma_f32_16x16x32_bf16 v[64:67], v[158:161], v[204:207], 0
	v_mfma_f32_16x16x32_bf16 v[116:119], v[154:157], v[176:179], v[116:119]
	v_mfma_f32_16x16x32_bf16 v[112:115], v[162:165], v[176:179], v[112:115]
	v_mfma_f32_16x16x32_bf16 v[100:103], v[154:157], v[184:187], v[100:103]
	v_mfma_f32_16x16x32_bf16 v[96:99], v[162:165], v[184:187], v[96:99]
	v_mfma_f32_16x16x32_bf16 v[84:87], v[154:157], v[200:203], v[84:87]
	v_mfma_f32_16x16x32_bf16 v[80:83], v[162:165], v[200:203], v[80:83]
	v_mfma_f32_16x16x32_bf16 v[68:71], v[154:157], v[208:211], v[68:71]
	v_mfma_f32_16x16x32_bf16 v[64:67], v[162:165], v[208:211], v[64:67]
	s_setprio 0
	s_barrier
; #define PG8_STAGE(bufoff, gbase, voff) do { _Pragma("unroll") for (int _i = 0; _i < 2; ++_i) \
;         __builtin_amdgcn_global_load_lds((const unsigned*)((const char*)(gbase) + (voff)[_i]), (PG8_LAS unsigned*)(lds + (bufoff) + ldsw + _i * 8192), 16, 0, 0); } while (0)
; #define PG8_LDA(dst, b, h) do { _Pragma("unroll") for (int m = 0; m < 4; ++m) _Pragma("unroll") for (int k = 0; k < 2; ++k) dst[m][k] = *(const PG8_LAS bf16x8*)(lds + PG8_SA(b, h) + aoff + m * 2048 + k * 1024); } while (0)
; #define PG8_MMA(ai, bj, At, Bt) do { __builtin_amdgcn_s_setprio(1); _Pragma("unroll") for (int m = 0; m < 4; ++m) _Pragma("unroll") for (int n = 0; n < 2; ++n) _Pragma("unroll") for (int k = 0; k < 2; ++k) \
;         acc[ai][bj][m][n] = __builtin_amdgcn_mfma_f32_16x16x32_bf16(Bt[n][k], At[m][k], acc[ai][bj][m][n], 0, 0, 0); __builtin_amdgcn_s_setprio(0); } while (0)
; #define PG8_WAIT_V(n) asm volatile("s_waitcnt vmcnt(" #n ")" ::: "memory")
; #define PG8_WAIT_L(n) asm volatile("s_waitcnt lgkmcnt(" #n ")" ::: "memory")
; #define PG8_BAR __builtin_amdgcn_s_barrier()
; #define PG8_SCHED __builtin_amdgcn_sched_barrier(0)
; template <class Epi, class Sched, bool ALIGN_EPI = false, bool SP2 = true>
; __device__ __forceinline__ void gemm_phase(PG8_LAS unsigned char* lds, const Gemm g, const Sched& S, const Epi& E) {
;     ...
;             PG8_LDA(At, 0, 1); PG8_STAGE(PG8_SB(0, 0), b2, voffB); PG8_STAGE(PG8_SB(0, 1), b2 + hstep, voffB); PG8_STAGE(PG8_SA(0, 0), a2, voffA);
;             PG8_WAIT_V(8); PG8_WAIT_L(0); PG8_BAR; PG8_MMA(1, 0, At, B0); PG8_MMA(1, 1, At, B1); PG8_BAR; PG8_SCHED;
	s_add_i32 s5, s14, s30
	v_lshl_add_u64 v[170:171], s[52:53], 0, v[194:195]
	s_mov_b32 m0, s5
	ds_read_b128 v[166:169], v175 offset:16384
	ds_read_b128 v[176:179], v175 offset:17408
	ds_read_b128 v[180:183], v175 offset:18432
	ds_read_b128 v[184:187], v175 offset:19456
	ds_read_b128 v[188:191], v175 offset:20480
	ds_read_b128 v[200:203], v175 offset:21504
	ds_read_b128 v[204:207], v175 offset:22528
	ds_read_b128 v[208:211], v175 offset:23552
	global_load_lds_dwordx4 v[170:171], off
	s_add_i32 m0, s5, 0x2000
	s_add_u32 s14, s52, 0x40000
	v_lshl_add_u64 v[198:199], s[52:53], 0, v[128:129]
	s_addc_u32 s15, s53, 0
	s_add_i32 s4, s4, s30
	global_load_lds_dwordx4 v[198:199], off
	v_lshl_add_u64 v[212:213], s[14:15], 0, v[194:195]
	s_mov_b32 m0, s4
	v_lshl_add_u64 v[214:215], s[84:85], 0, v[128:129]
	global_load_lds_dwordx4 v[212:213], off
	v_lshl_add_u64 v[212:213], s[14:15], 0, v[128:129]
	s_add_i32 m0, s4, 0x2000
	s_nop 0
	global_load_lds_dwordx4 v[212:213], off
	v_lshl_add_u64 v[212:213], s[84:85], 0, v[194:195]
	s_mov_b32 m0, s31
	s_nop 0
	global_load_lds_dwordx4 v[212:213], off
	s_mov_b32 m0, s34
	s_nop 0
	global_load_lds_dwordx4 v[214:215], off
	s_waitcnt vmcnt(8)
	s_waitcnt lgkmcnt(0)
	s_setprio 1
	s_barrier
	v_mfma_f32_16x16x32_bf16 v[60:63], v[134:137], v[166:169], 0
	v_mfma_f32_16x16x32_bf16 v[56:59], v[142:145], v[166:169], 0
	v_mfma_f32_16x16x32_bf16 v[44:47], v[134:137], v[180:183], 0
	v_mfma_f32_16x16x32_bf16 v[40:43], v[142:145], v[180:183], 0
	v_mfma_f32_16x16x32_bf16 v[28:31], v[134:137], v[188:191], 0
	v_mfma_f32_16x16x32_bf16 v[24:27], v[142:145], v[188:191], 0
	v_mfma_f32_16x16x32_bf16 v[12:15], v[134:137], v[204:207], 0
	v_mfma_f32_16x16x32_bf16 v[8:11], v[142:145], v[204:207], 0
	v_mfma_f32_16x16x32_bf16 v[60:63], v[138:141], v[176:179], v[60:63]
	v_mfma_f32_16x16x32_bf16 v[56:59], v[146:149], v[176:179], v[56:59]
	v_mfma_f32_16x16x32_bf16 v[44:47], v[138:141], v[184:187], v[44:47]
	v_mfma_f32_16x16x32_bf16 v[40:43], v[146:149], v[184:187], v[40:43]
	v_mfma_f32_16x16x32_bf16 v[28:31], v[138:141], v[200:203], v[28:31]
	v_mfma_f32_16x16x32_bf16 v[24:27], v[146:149], v[200:203], v[24:27]
	v_mfma_f32_16x16x32_bf16 v[12:15], v[138:141], v[208:211], v[12:15]
	v_mfma_f32_16x16x32_bf16 v[8:11], v[146:149], v[208:211], v[8:11]
	s_setprio 0
	s_setprio 1
	v_mfma_f32_16x16x32_bf16 v[52:55], v[150:153], v[166:169], 0
	v_mfma_f32_16x16x32_bf16 v[48:51], v[158:161], v[166:169], 0
	v_mfma_f32_16x16x32_bf16 v[36:39], v[150:153], v[180:183], 0
	v_mfma_f32_16x16x32_bf16 v[32:35], v[158:161], v[180:183], 0
	v_mfma_f32_16x16x32_bf16 v[20:23], v[150:153], v[188:191], 0
	v_mfma_f32_16x16x32_bf16 v[16:19], v[158:161], v[188:191], 0
	v_mfma_f32_16x16x32_bf16 v[4:7], v[150:153], v[204:207], 0
	v_mfma_f32_16x16x32_bf16 v[0:3], v[158:161], v[204:207], 0
	v_mfma_f32_16x16x32_bf16 v[52:55], v[154:157], v[176:179], v[52:55]
	v_mfma_f32_16x16x32_bf16 v[48:51], v[162:165], v[176:179], v[48:51]
	v_mfma_f32_16x16x32_bf16 v[36:39], v[154:157], v[184:187], v[36:39]
	v_mfma_f32_16x16x32_bf16 v[32:35], v[162:165], v[184:187], v[32:35]
	v_mfma_f32_16x16x32_bf16 v[20:23], v[154:157], v[200:203], v[20:23]
	v_mfma_f32_16x16x32_bf16 v[16:19], v[162:165], v[200:203], v[16:19]
	v_mfma_f32_16x16x32_bf16 v[4:7], v[154:157], v[208:211], v[4:7]
	v_mfma_f32_16x16x32_bf16 v[0:3], v[162:165], v[208:211], v[0:3]
	s_setprio 0
	s_barrier
	s_branch .Lmo_s3
